# compress_unit first GEMM: K-loop unrolled with the next iteration's 18 loads issued before the current iteration's MFMAs
# speedup vs baseline: 1.0068x; 1.0068x over previous
.LBB0_343:
	v_ashrrev_i32_e32 v40, 1, v58
	v_mad_i64_i32 v[40:41], s[22:23], v40, s63, v[36:37]
	v_add_u32_e32 v59, 1, v58
	v_ashrrev_i32_e32 v59, 1, v59
	v_mad_i64_i32 v[42:43], s[22:23], v59, s63, v[36:37]
	global_load_dwordx4 v[60:63], v[40:41], off
	global_load_dwordx4 v[64:67], v[42:43], off offset:64
	v_lshl_add_u64 v[44:45], v[38:39], 0, s[12:13]
	s_mov_b32 s14, 0x3100000
	v_add_co_u32_e32 v132, vcc, s14, v44
	s_nop 1
	v_addc_co_u32_e32 v133, vcc, 0, v45, vcc
	global_load_dwordx4 v[68:71], v[132:133], off
	global_load_dwordx4 v[100:103], v[132:133], off offset:64
	s_mov_b32 s14, 0x3110000
	v_add_co_u32_e32 v134, vcc, s14, v44
	s_nop 1
	v_addc_co_u32_e32 v135, vcc, 0, v45, vcc
	global_load_dwordx4 v[72:75], v[134:135], off
	global_load_dwordx4 v[104:107], v[134:135], off offset:64
	s_mov_b32 s14, 0x3120000
	v_add_co_u32_e32 v136, vcc, s14, v44
	s_nop 1
	v_addc_co_u32_e32 v137, vcc, 0, v45, vcc
	global_load_dwordx4 v[76:79], v[136:137], off
	global_load_dwordx4 v[108:111], v[136:137], off offset:64
	s_mov_b32 s14, 0x3130000
	v_add_co_u32_e32 v138, vcc, s14, v44
	s_nop 1
	v_addc_co_u32_e32 v139, vcc, 0, v45, vcc
	global_load_dwordx4 v[80:83], v[138:139], off
	global_load_dwordx4 v[112:115], v[138:139], off offset:64
	s_mov_b32 s14, 0x3140000
	v_add_co_u32_e32 v140, vcc, s14, v44
	s_nop 1
	v_addc_co_u32_e32 v141, vcc, 0, v45, vcc
	global_load_dwordx4 v[84:87], v[140:141], off
	global_load_dwordx4 v[116:119], v[140:141], off offset:64
	s_mov_b32 s14, 0x3150000
	v_add_co_u32_e32 v142, vcc, s14, v44
	s_nop 1
	v_addc_co_u32_e32 v143, vcc, 0, v45, vcc
	global_load_dwordx4 v[88:91], v[142:143], off
	global_load_dwordx4 v[120:123], v[142:143], off offset:64
	s_mov_b32 s14, 0x3160000
	v_add_co_u32_e32 v144, vcc, s14, v44
	s_nop 1
	v_addc_co_u32_e32 v145, vcc, 0, v45, vcc
	global_load_dwordx4 v[92:95], v[144:145], off
	global_load_dwordx4 v[124:127], v[144:145], off offset:64
	s_mov_b32 s14, 0x3170000
	v_add_co_u32_e32 v146, vcc, s14, v44
	s_nop 1
	v_addc_co_u32_e32 v147, vcc, 0, v45, vcc
	global_load_dwordx4 v[96:99], v[146:147], off
	global_load_dwordx4 v[128:131], v[146:147], off offset:64
	s_add_u32 s12, s12, 0x80
	s_addc_u32 s13, s13, 0
	v_add_u32_e32 v58, 2, v58
	v_ashrrev_i32_e32 v40, 1, v58
	v_mad_i64_i32 v[40:41], s[22:23], v40, s63, v[36:37]
	v_add_u32_e32 v59, 1, v58
	v_ashrrev_i32_e32 v59, 1, v59
	v_mad_i64_i32 v[42:43], s[22:23], v59, s63, v[36:37]
	global_load_dwordx4 v[240:243], v[40:41], off
	global_load_dwordx4 v[244:247], v[42:43], off offset:64
	v_lshl_add_u64 v[44:45], v[38:39], 0, s[12:13]
	s_mov_b32 s14, 0x3100000
	v_add_co_u32_e32 v132, vcc, s14, v44
	s_nop 1
	v_addc_co_u32_e32 v133, vcc, 0, v45, vcc
	global_load_dwordx4 v[168:171], v[132:133], off
	global_load_dwordx4 v[212:215], v[132:133], off offset:64
	s_mov_b32 s14, 0x3110000
	v_add_co_u32_e32 v134, vcc, s14, v44
	s_nop 1
	v_addc_co_u32_e32 v135, vcc, 0, v45, vcc
	global_load_dwordx4 v[172:175], v[134:135], off
	global_load_dwordx4 v[216:219], v[134:135], off offset:64
	s_mov_b32 s14, 0x3120000
	v_add_co_u32_e32 v136, vcc, s14, v44
	s_nop 1
	v_addc_co_u32_e32 v137, vcc, 0, v45, vcc
	global_load_dwordx4 v[176:179], v[136:137], off
	global_load_dwordx4 v[220:223], v[136:137], off offset:64
	s_mov_b32 s14, 0x3130000
	v_add_co_u32_e32 v138, vcc, s14, v44
	s_nop 1
	v_addc_co_u32_e32 v139, vcc, 0, v45, vcc
	global_load_dwordx4 v[180:183], v[138:139], off
	global_load_dwordx4 v[224:227], v[138:139], off offset:64
	s_mov_b32 s14, 0x3140000
	v_add_co_u32_e32 v140, vcc, s14, v44
	s_nop 1
	v_addc_co_u32_e32 v141, vcc, 0, v45, vcc
	global_load_dwordx4 v[184:187], v[140:141], off
	global_load_dwordx4 v[228:231], v[140:141], off offset:64
	s_mov_b32 s14, 0x3150000
	v_add_co_u32_e32 v142, vcc, s14, v44
	s_nop 1
	v_addc_co_u32_e32 v143, vcc, 0, v45, vcc
	global_load_dwordx4 v[188:191], v[142:143], off
	global_load_dwordx4 v[232:235], v[142:143], off offset:64
	s_mov_b32 s14, 0x3160000
	v_add_co_u32_e32 v144, vcc, s14, v44
	s_nop 1
	v_addc_co_u32_e32 v145, vcc, 0, v45, vcc
	global_load_dwordx4 v[192:195], v[144:145], off
	global_load_dwordx4 v[236:239], v[144:145], off offset:64
	s_mov_b32 s14, 0x3170000
	v_add_co_u32_e32 v146, vcc, s14, v44
	s_nop 1
	v_addc_co_u32_e32 v147, vcc, 0, v45, vcc
	global_load_dwordx4 v[208:211], v[146:147], off
	global_load_dwordx4 v[248:251], v[146:147], off offset:64
	s_add_u32 s12, s12, 0x80
	s_addc_u32 s13, s13, 0
	v_add_u32_e32 v58, 2, v58
	s_waitcnt vmcnt(33)
	v_mfma_f32_16x16x32_bf16 v[0:3], v[60:63], v[68:71], v[0:3]
	s_waitcnt vmcnt(31)
	v_mfma_f32_16x16x32_bf16 v[4:7], v[60:63], v[72:75], v[4:7]
	s_waitcnt vmcnt(29)
	v_mfma_f32_16x16x32_bf16 v[8:11], v[60:63], v[76:79], v[8:11]
	s_waitcnt vmcnt(27)
	v_mfma_f32_16x16x32_bf16 v[12:15], v[60:63], v[80:83], v[12:15]
	s_waitcnt vmcnt(25)
	v_mfma_f32_16x16x32_bf16 v[16:19], v[60:63], v[84:87], v[16:19]
	s_waitcnt vmcnt(23)
	v_mfma_f32_16x16x32_bf16 v[20:23], v[60:63], v[88:91], v[20:23]
	s_waitcnt vmcnt(21)
	v_mfma_f32_16x16x32_bf16 v[24:27], v[60:63], v[92:95], v[24:27]
	s_waitcnt vmcnt(19)
	v_mfma_f32_16x16x32_bf16 v[28:31], v[60:63], v[96:99], v[28:31]
	s_waitcnt vmcnt(18)
	v_mfma_f32_16x16x32_bf16 v[0:3], v[64:67], v[100:103], v[0:3]
	v_mfma_f32_16x16x32_bf16 v[4:7], v[64:67], v[104:107], v[4:7]
	v_mfma_f32_16x16x32_bf16 v[8:11], v[64:67], v[108:111], v[8:11]
	v_mfma_f32_16x16x32_bf16 v[12:15], v[64:67], v[112:115], v[12:15]
	v_mfma_f32_16x16x32_bf16 v[16:19], v[64:67], v[116:119], v[16:19]
	v_mfma_f32_16x16x32_bf16 v[20:23], v[64:67], v[120:123], v[20:23]
	v_mfma_f32_16x16x32_bf16 v[24:27], v[64:67], v[124:127], v[24:27]
	v_mfma_f32_16x16x32_bf16 v[28:31], v[64:67], v[128:131], v[28:31]
	v_ashrrev_i32_e32 v40, 1, v58
	v_mad_i64_i32 v[40:41], s[22:23], v40, s63, v[36:37]
	v_add_u32_e32 v59, 1, v58
	v_ashrrev_i32_e32 v59, 1, v59
	v_mad_i64_i32 v[42:43], s[22:23], v59, s63, v[36:37]
	global_load_dwordx4 v[60:63], v[40:41], off
	global_load_dwordx4 v[64:67], v[42:43], off offset:64
	v_lshl_add_u64 v[44:45], v[38:39], 0, s[12:13]
	s_mov_b32 s14, 0x3100000
	v_add_co_u32_e32 v132, vcc, s14, v44
	s_nop 1
	v_addc_co_u32_e32 v133, vcc, 0, v45, vcc
	global_load_dwordx4 v[68:71], v[132:133], off
	global_load_dwordx4 v[100:103], v[132:133], off offset:64
	s_mov_b32 s14, 0x3110000
	v_add_co_u32_e32 v134, vcc, s14, v44
	s_nop 1
	v_addc_co_u32_e32 v135, vcc, 0, v45, vcc
	global_load_dwordx4 v[72:75], v[134:135], off
	global_load_dwordx4 v[104:107], v[134:135], off offset:64
	s_mov_b32 s14, 0x3120000
	v_add_co_u32_e32 v136, vcc, s14, v44
	s_nop 1
	v_addc_co_u32_e32 v137, vcc, 0, v45, vcc
	global_load_dwordx4 v[76:79], v[136:137], off
	global_load_dwordx4 v[108:111], v[136:137], off offset:64
	s_mov_b32 s14, 0x3130000
	v_add_co_u32_e32 v138, vcc, s14, v44
	s_nop 1
	v_addc_co_u32_e32 v139, vcc, 0, v45, vcc
	global_load_dwordx4 v[80:83], v[138:139], off
	global_load_dwordx4 v[112:115], v[138:139], off offset:64
	s_mov_b32 s14, 0x3140000
	v_add_co_u32_e32 v140, vcc, s14, v44
	s_nop 1
	v_addc_co_u32_e32 v141, vcc, 0, v45, vcc
	global_load_dwordx4 v[84:87], v[140:141], off
	global_load_dwordx4 v[116:119], v[140:141], off offset:64
	s_mov_b32 s14, 0x3150000
	v_add_co_u32_e32 v142, vcc, s14, v44
	s_nop 1
	v_addc_co_u32_e32 v143, vcc, 0, v45, vcc
	global_load_dwordx4 v[88:91], v[142:143], off
	global_load_dwordx4 v[120:123], v[142:143], off offset:64
	s_mov_b32 s14, 0x3160000
	v_add_co_u32_e32 v144, vcc, s14, v44
	s_nop 1
	v_addc_co_u32_e32 v145, vcc, 0, v45, vcc
	global_load_dwordx4 v[92:95], v[144:145], off
	global_load_dwordx4 v[124:127], v[144:145], off offset:64
	s_mov_b32 s14, 0x3170000
	v_add_co_u32_e32 v146, vcc, s14, v44
	s_nop 1
	v_addc_co_u32_e32 v147, vcc, 0, v45, vcc
	global_load_dwordx4 v[96:99], v[146:147], off
	global_load_dwordx4 v[128:131], v[146:147], off offset:64
	s_add_u32 s12, s12, 0x80
	s_addc_u32 s13, s13, 0
	v_add_u32_e32 v58, 2, v58
	s_waitcnt vmcnt(33)
	v_mfma_f32_16x16x32_bf16 v[0:3], v[240:243], v[168:171], v[0:3]
	s_waitcnt vmcnt(31)
	v_mfma_f32_16x16x32_bf16 v[4:7], v[240:243], v[172:175], v[4:7]
	s_waitcnt vmcnt(29)
	v_mfma_f32_16x16x32_bf16 v[8:11], v[240:243], v[176:179], v[8:11]
	s_waitcnt vmcnt(27)
	v_mfma_f32_16x16x32_bf16 v[12:15], v[240:243], v[180:183], v[12:15]
	s_waitcnt vmcnt(25)
	v_mfma_f32_16x16x32_bf16 v[16:19], v[240:243], v[184:187], v[16:19]
	s_waitcnt vmcnt(23)
	v_mfma_f32_16x16x32_bf16 v[20:23], v[240:243], v[188:191], v[20:23]
	s_waitcnt vmcnt(21)
	v_mfma_f32_16x16x32_bf16 v[24:27], v[240:243], v[192:195], v[24:27]
	s_waitcnt vmcnt(19)
	v_mfma_f32_16x16x32_bf16 v[28:31], v[240:243], v[208:211], v[28:31]
	s_waitcnt vmcnt(18)
	v_mfma_f32_16x16x32_bf16 v[0:3], v[244:247], v[212:215], v[0:3]
	v_mfma_f32_16x16x32_bf16 v[4:7], v[244:247], v[216:219], v[4:7]
	v_mfma_f32_16x16x32_bf16 v[8:11], v[244:247], v[220:223], v[8:11]
	v_mfma_f32_16x16x32_bf16 v[12:15], v[244:247], v[224:227], v[12:15]
	v_mfma_f32_16x16x32_bf16 v[16:19], v[244:247], v[228:231], v[16:19]
	v_mfma_f32_16x16x32_bf16 v[20:23], v[244:247], v[232:235], v[20:23]
	v_mfma_f32_16x16x32_bf16 v[24:27], v[244:247], v[236:239], v[24:27]
	v_mfma_f32_16x16x32_bf16 v[28:31], v[244:247], v[248:251], v[28:31]
	v_ashrrev_i32_e32 v40, 1, v58
	v_mad_i64_i32 v[40:41], s[22:23], v40, s63, v[36:37]
	v_add_u32_e32 v59, 1, v58
	v_ashrrev_i32_e32 v59, 1, v59
	v_mad_i64_i32 v[42:43], s[22:23], v59, s63, v[36:37]
	global_load_dwordx4 v[240:243], v[40:41], off
	global_load_dwordx4 v[244:247], v[42:43], off offset:64
	v_lshl_add_u64 v[44:45], v[38:39], 0, s[12:13]
	s_mov_b32 s14, 0x3100000
	v_add_co_u32_e32 v132, vcc, s14, v44
	s_nop 1
	v_addc_co_u32_e32 v133, vcc, 0, v45, vcc
	global_load_dwordx4 v[168:171], v[132:133], off
	global_load_dwordx4 v[212:215], v[132:133], off offset:64
	s_mov_b32 s14, 0x3110000
	v_add_co_u32_e32 v134, vcc, s14, v44
	s_nop 1
	v_addc_co_u32_e32 v135, vcc, 0, v45, vcc
	global_load_dwordx4 v[172:175], v[134:135], off
	global_load_dwordx4 v[216:219], v[134:135], off offset:64
	s_mov_b32 s14, 0x3120000
	v_add_co_u32_e32 v136, vcc, s14, v44
	s_nop 1
	v_addc_co_u32_e32 v137, vcc, 0, v45, vcc
	global_load_dwordx4 v[176:179], v[136:137], off
	global_load_dwordx4 v[220:223], v[136:137], off offset:64
	s_mov_b32 s14, 0x3130000
	v_add_co_u32_e32 v138, vcc, s14, v44
	s_nop 1
	v_addc_co_u32_e32 v139, vcc, 0, v45, vcc
	global_load_dwordx4 v[180:183], v[138:139], off
	global_load_dwordx4 v[224:227], v[138:139], off offset:64
	s_mov_b32 s14, 0x3140000
	v_add_co_u32_e32 v140, vcc, s14, v44
	s_nop 1
	v_addc_co_u32_e32 v141, vcc, 0, v45, vcc
	global_load_dwordx4 v[184:187], v[140:141], off
	global_load_dwordx4 v[228:231], v[140:141], off offset:64
	s_mov_b32 s14, 0x3150000
	v_add_co_u32_e32 v142, vcc, s14, v44
	s_nop 1
	v_addc_co_u32_e32 v143, vcc, 0, v45, vcc
	global_load_dwordx4 v[188:191], v[142:143], off
	global_load_dwordx4 v[232:235], v[142:143], off offset:64
	s_mov_b32 s14, 0x3160000
	v_add_co_u32_e32 v144, vcc, s14, v44
	s_nop 1
	v_addc_co_u32_e32 v145, vcc, 0, v45, vcc
	global_load_dwordx4 v[192:195], v[144:145], off
	global_load_dwordx4 v[236:239], v[144:145], off offset:64
	s_mov_b32 s14, 0x3170000
	v_add_co_u32_e32 v146, vcc, s14, v44
	s_nop 1
	v_addc_co_u32_e32 v147, vcc, 0, v45, vcc
	global_load_dwordx4 v[208:211], v[146:147], off
	global_load_dwordx4 v[248:251], v[146:147], off offset:64
	s_add_u32 s12, s12, 0x80
	s_addc_u32 s13, s13, 0
	v_add_u32_e32 v58, 2, v58
	s_waitcnt vmcnt(33)
	v_mfma_f32_16x16x32_bf16 v[0:3], v[60:63], v[68:71], v[0:3]
	s_waitcnt vmcnt(31)
	v_mfma_f32_16x16x32_bf16 v[4:7], v[60:63], v[72:75], v[4:7]
	s_waitcnt vmcnt(29)
	v_mfma_f32_16x16x32_bf16 v[8:11], v[60:63], v[76:79], v[8:11]
	s_waitcnt vmcnt(27)
	v_mfma_f32_16x16x32_bf16 v[12:15], v[60:63], v[80:83], v[12:15]
	s_waitcnt vmcnt(25)
	v_mfma_f32_16x16x32_bf16 v[16:19], v[60:63], v[84:87], v[16:19]
	s_waitcnt vmcnt(23)
	v_mfma_f32_16x16x32_bf16 v[20:23], v[60:63], v[88:91], v[20:23]
	s_waitcnt vmcnt(21)
	v_mfma_f32_16x16x32_bf16 v[24:27], v[60:63], v[92:95], v[24:27]
	s_waitcnt vmcnt(19)
	v_mfma_f32_16x16x32_bf16 v[28:31], v[60:63], v[96:99], v[28:31]
	s_waitcnt vmcnt(18)
	v_mfma_f32_16x16x32_bf16 v[0:3], v[64:67], v[100:103], v[0:3]
	v_mfma_f32_16x16x32_bf16 v[4:7], v[64:67], v[104:107], v[4:7]
	v_mfma_f32_16x16x32_bf16 v[8:11], v[64:67], v[108:111], v[8:11]
	v_mfma_f32_16x16x32_bf16 v[12:15], v[64:67], v[112:115], v[12:15]
	v_mfma_f32_16x16x32_bf16 v[16:19], v[64:67], v[116:119], v[16:19]
	v_mfma_f32_16x16x32_bf16 v[20:23], v[64:67], v[120:123], v[20:23]
	v_mfma_f32_16x16x32_bf16 v[24:27], v[64:67], v[124:127], v[24:27]
	v_mfma_f32_16x16x32_bf16 v[28:31], v[64:67], v[128:131], v[28:31]
	v_ashrrev_i32_e32 v40, 1, v58
	v_mad_i64_i32 v[40:41], s[22:23], v40, s63, v[36:37]
	v_add_u32_e32 v59, 1, v58
	v_ashrrev_i32_e32 v59, 1, v59
	v_mad_i64_i32 v[42:43], s[22:23], v59, s63, v[36:37]
	global_load_dwordx4 v[60:63], v[40:41], off
	global_load_dwordx4 v[64:67], v[42:43], off offset:64
	v_lshl_add_u64 v[44:45], v[38:39], 0, s[12:13]
	s_mov_b32 s14, 0x3100000
	v_add_co_u32_e32 v132, vcc, s14, v44
	s_nop 1
	v_addc_co_u32_e32 v133, vcc, 0, v45, vcc
	global_load_dwordx4 v[68:71], v[132:133], off
	global_load_dwordx4 v[100:103], v[132:133], off offset:64
	s_mov_b32 s14, 0x3110000
	v_add_co_u32_e32 v134, vcc, s14, v44
	s_nop 1
	v_addc_co_u32_e32 v135, vcc, 0, v45, vcc
	global_load_dwordx4 v[72:75], v[134:135], off
	global_load_dwordx4 v[104:107], v[134:135], off offset:64
	s_mov_b32 s14, 0x3120000
	v_add_co_u32_e32 v136, vcc, s14, v44
	s_nop 1
	v_addc_co_u32_e32 v137, vcc, 0, v45, vcc
	global_load_dwordx4 v[76:79], v[136:137], off
	global_load_dwordx4 v[108:111], v[136:137], off offset:64
	s_mov_b32 s14, 0x3130000
	v_add_co_u32_e32 v138, vcc, s14, v44
	s_nop 1
	v_addc_co_u32_e32 v139, vcc, 0, v45, vcc
	global_load_dwordx4 v[80:83], v[138:139], off
	global_load_dwordx4 v[112:115], v[138:139], off offset:64
	s_mov_b32 s14, 0x3140000
	v_add_co_u32_e32 v140, vcc, s14, v44
	s_nop 1
	v_addc_co_u32_e32 v141, vcc, 0, v45, vcc
	global_load_dwordx4 v[84:87], v[140:141], off
	global_load_dwordx4 v[116:119], v[140:141], off offset:64
	s_mov_b32 s14, 0x3150000
	v_add_co_u32_e32 v142, vcc, s14, v44
	s_nop 1
	v_addc_co_u32_e32 v143, vcc, 0, v45, vcc
	global_load_dwordx4 v[88:91], v[142:143], off
	global_load_dwordx4 v[120:123], v[142:143], off offset:64
	s_mov_b32 s14, 0x3160000
	v_add_co_u32_e32 v144, vcc, s14, v44
	s_nop 1
	v_addc_co_u32_e32 v145, vcc, 0, v45, vcc
	global_load_dwordx4 v[92:95], v[144:145], off
	global_load_dwordx4 v[124:127], v[144:145], off offset:64
	s_mov_b32 s14, 0x3170000
	v_add_co_u32_e32 v146, vcc, s14, v44
	s_nop 1
	v_addc_co_u32_e32 v147, vcc, 0, v45, vcc
	global_load_dwordx4 v[96:99], v[146:147], off
	global_load_dwordx4 v[128:131], v[146:147], off offset:64
	s_add_u32 s12, s12, 0x80
	s_addc_u32 s13, s13, 0
	v_add_u32_e32 v58, 2, v58
	s_waitcnt vmcnt(33)
	v_mfma_f32_16x16x32_bf16 v[0:3], v[240:243], v[168:171], v[0:3]
	s_waitcnt vmcnt(31)
	v_mfma_f32_16x16x32_bf16 v[4:7], v[240:243], v[172:175], v[4:7]
	s_waitcnt vmcnt(29)
	v_mfma_f32_16x16x32_bf16 v[8:11], v[240:243], v[176:179], v[8:11]
	s_waitcnt vmcnt(27)
	v_mfma_f32_16x16x32_bf16 v[12:15], v[240:243], v[180:183], v[12:15]
	s_waitcnt vmcnt(25)
	v_mfma_f32_16x16x32_bf16 v[16:19], v[240:243], v[184:187], v[16:19]
	s_waitcnt vmcnt(23)
	v_mfma_f32_16x16x32_bf16 v[20:23], v[240:243], v[188:191], v[20:23]
	s_waitcnt vmcnt(21)
	v_mfma_f32_16x16x32_bf16 v[24:27], v[240:243], v[192:195], v[24:27]
	s_waitcnt vmcnt(19)
	v_mfma_f32_16x16x32_bf16 v[28:31], v[240:243], v[208:211], v[28:31]
	s_waitcnt vmcnt(18)
	v_mfma_f32_16x16x32_bf16 v[0:3], v[244:247], v[212:215], v[0:3]
	v_mfma_f32_16x16x32_bf16 v[4:7], v[244:247], v[216:219], v[4:7]
	v_mfma_f32_16x16x32_bf16 v[8:11], v[244:247], v[220:223], v[8:11]
	v_mfma_f32_16x16x32_bf16 v[12:15], v[244:247], v[224:227], v[12:15]
	v_mfma_f32_16x16x32_bf16 v[16:19], v[244:247], v[228:231], v[16:19]
	v_mfma_f32_16x16x32_bf16 v[20:23], v[244:247], v[232:235], v[20:23]
	v_mfma_f32_16x16x32_bf16 v[24:27], v[244:247], v[236:239], v[24:27]
	v_mfma_f32_16x16x32_bf16 v[28:31], v[244:247], v[248:251], v[28:31]
	v_ashrrev_i32_e32 v40, 1, v58
	v_mad_i64_i32 v[40:41], s[22:23], v40, s63, v[36:37]
	v_add_u32_e32 v59, 1, v58
	v_ashrrev_i32_e32 v59, 1, v59
	v_mad_i64_i32 v[42:43], s[22:23], v59, s63, v[36:37]
	global_load_dwordx4 v[240:243], v[40:41], off
	global_load_dwordx4 v[244:247], v[42:43], off offset:64
	v_lshl_add_u64 v[44:45], v[38:39], 0, s[12:13]
	s_mov_b32 s14, 0x3100000
	v_add_co_u32_e32 v132, vcc, s14, v44
	s_nop 1
	v_addc_co_u32_e32 v133, vcc, 0, v45, vcc
	global_load_dwordx4 v[168:171], v[132:133], off
	global_load_dwordx4 v[212:215], v[132:133], off offset:64
	s_mov_b32 s14, 0x3110000
	v_add_co_u32_e32 v134, vcc, s14, v44
	s_nop 1
	v_addc_co_u32_e32 v135, vcc, 0, v45, vcc
	global_load_dwordx4 v[172:175], v[134:135], off
	global_load_dwordx4 v[216:219], v[134:135], off offset:64
	s_mov_b32 s14, 0x3120000
	v_add_co_u32_e32 v136, vcc, s14, v44
	s_nop 1
	v_addc_co_u32_e32 v137, vcc, 0, v45, vcc
	global_load_dwordx4 v[176:179], v[136:137], off
	global_load_dwordx4 v[220:223], v[136:137], off offset:64
	s_mov_b32 s14, 0x3130000
	v_add_co_u32_e32 v138, vcc, s14, v44
	s_nop 1
	v_addc_co_u32_e32 v139, vcc, 0, v45, vcc
	global_load_dwordx4 v[180:183], v[138:139], off
	global_load_dwordx4 v[224:227], v[138:139], off offset:64
	s_mov_b32 s14, 0x3140000
	v_add_co_u32_e32 v140, vcc, s14, v44
	s_nop 1
	v_addc_co_u32_e32 v141, vcc, 0, v45, vcc
	global_load_dwordx4 v[184:187], v[140:141], off
	global_load_dwordx4 v[228:231], v[140:141], off offset:64
	s_mov_b32 s14, 0x3150000
	v_add_co_u32_e32 v142, vcc, s14, v44
	s_nop 1
	v_addc_co_u32_e32 v143, vcc, 0, v45, vcc
	global_load_dwordx4 v[188:191], v[142:143], off
	global_load_dwordx4 v[232:235], v[142:143], off offset:64
	s_mov_b32 s14, 0x3160000
	v_add_co_u32_e32 v144, vcc, s14, v44
	s_nop 1
	v_addc_co_u32_e32 v145, vcc, 0, v45, vcc
	global_load_dwordx4 v[192:195], v[144:145], off
	global_load_dwordx4 v[236:239], v[144:145], off offset:64
	s_mov_b32 s14, 0x3170000
	v_add_co_u32_e32 v146, vcc, s14, v44
	s_nop 1
	v_addc_co_u32_e32 v147, vcc, 0, v45, vcc
	global_load_dwordx4 v[208:211], v[146:147], off
	global_load_dwordx4 v[248:251], v[146:147], off offset:64
	s_add_u32 s12, s12, 0x80
	s_addc_u32 s13, s13, 0
	v_add_u32_e32 v58, 2, v58
	s_waitcnt vmcnt(33)
	v_mfma_f32_16x16x32_bf16 v[0:3], v[60:63], v[68:71], v[0:3]
	s_waitcnt vmcnt(31)
	v_mfma_f32_16x16x32_bf16 v[4:7], v[60:63], v[72:75], v[4:7]
	s_waitcnt vmcnt(29)
	v_mfma_f32_16x16x32_bf16 v[8:11], v[60:63], v[76:79], v[8:11]
	s_waitcnt vmcnt(27)
	v_mfma_f32_16x16x32_bf16 v[12:15], v[60:63], v[80:83], v[12:15]
	s_waitcnt vmcnt(25)
	v_mfma_f32_16x16x32_bf16 v[16:19], v[60:63], v[84:87], v[16:19]
	s_waitcnt vmcnt(23)
	v_mfma_f32_16x16x32_bf16 v[20:23], v[60:63], v[88:91], v[20:23]
	s_waitcnt vmcnt(21)
	v_mfma_f32_16x16x32_bf16 v[24:27], v[60:63], v[92:95], v[24:27]
	s_waitcnt vmcnt(19)
	v_mfma_f32_16x16x32_bf16 v[28:31], v[60:63], v[96:99], v[28:31]
	s_waitcnt vmcnt(18)
	v_mfma_f32_16x16x32_bf16 v[0:3], v[64:67], v[100:103], v[0:3]
	v_mfma_f32_16x16x32_bf16 v[4:7], v[64:67], v[104:107], v[4:7]
	v_mfma_f32_16x16x32_bf16 v[8:11], v[64:67], v[108:111], v[8:11]
	v_mfma_f32_16x16x32_bf16 v[12:15], v[64:67], v[112:115], v[12:15]
	v_mfma_f32_16x16x32_bf16 v[16:19], v[64:67], v[116:119], v[16:19]
	v_mfma_f32_16x16x32_bf16 v[20:23], v[64:67], v[120:123], v[20:23]
	v_mfma_f32_16x16x32_bf16 v[24:27], v[64:67], v[124:127], v[24:27]
	v_mfma_f32_16x16x32_bf16 v[28:31], v[64:67], v[128:131], v[28:31]
	v_ashrrev_i32_e32 v40, 1, v58
	v_mad_i64_i32 v[40:41], s[22:23], v40, s63, v[36:37]
	v_add_u32_e32 v59, 1, v58
	v_ashrrev_i32_e32 v59, 1, v59
	v_mad_i64_i32 v[42:43], s[22:23], v59, s63, v[36:37]
	global_load_dwordx4 v[60:63], v[40:41], off
	global_load_dwordx4 v[64:67], v[42:43], off offset:64
	v_lshl_add_u64 v[44:45], v[38:39], 0, s[12:13]
	s_mov_b32 s14, 0x3100000
	v_add_co_u32_e32 v132, vcc, s14, v44
	s_nop 1
	v_addc_co_u32_e32 v133, vcc, 0, v45, vcc
	global_load_dwordx4 v[68:71], v[132:133], off
	global_load_dwordx4 v[100:103], v[132:133], off offset:64
	s_mov_b32 s14, 0x3110000
	v_add_co_u32_e32 v134, vcc, s14, v44
	s_nop 1
	v_addc_co_u32_e32 v135, vcc, 0, v45, vcc
	global_load_dwordx4 v[72:75], v[134:135], off
	global_load_dwordx4 v[104:107], v[134:135], off offset:64
	s_mov_b32 s14, 0x3120000
	v_add_co_u32_e32 v136, vcc, s14, v44
	s_nop 1
	v_addc_co_u32_e32 v137, vcc, 0, v45, vcc
	global_load_dwordx4 v[76:79], v[136:137], off
	global_load_dwordx4 v[108:111], v[136:137], off offset:64
	s_mov_b32 s14, 0x3130000
	v_add_co_u32_e32 v138, vcc, s14, v44
	s_nop 1
	v_addc_co_u32_e32 v139, vcc, 0, v45, vcc
	global_load_dwordx4 v[80:83], v[138:139], off
	global_load_dwordx4 v[112:115], v[138:139], off offset:64
	s_mov_b32 s14, 0x3140000
	v_add_co_u32_e32 v140, vcc, s14, v44
	s_nop 1
	v_addc_co_u32_e32 v141, vcc, 0, v45, vcc
	global_load_dwordx4 v[84:87], v[140:141], off
	global_load_dwordx4 v[116:119], v[140:141], off offset:64
	s_mov_b32 s14, 0x3150000
	v_add_co_u32_e32 v142, vcc, s14, v44
	s_nop 1
	v_addc_co_u32_e32 v143, vcc, 0, v45, vcc
	global_load_dwordx4 v[88:91], v[142:143], off
	global_load_dwordx4 v[120:123], v[142:143], off offset:64
	s_mov_b32 s14, 0x3160000
	v_add_co_u32_e32 v144, vcc, s14, v44
	s_nop 1
	v_addc_co_u32_e32 v145, vcc, 0, v45, vcc
	global_load_dwordx4 v[92:95], v[144:145], off
	global_load_dwordx4 v[124:127], v[144:145], off offset:64
	s_mov_b32 s14, 0x3170000
	v_add_co_u32_e32 v146, vcc, s14, v44
	s_nop 1
	v_addc_co_u32_e32 v147, vcc, 0, v45, vcc
	global_load_dwordx4 v[96:99], v[146:147], off
	global_load_dwordx4 v[128:131], v[146:147], off offset:64
	s_add_u32 s12, s12, 0x80
	s_addc_u32 s13, s13, 0
	v_add_u32_e32 v58, 2, v58
	s_waitcnt vmcnt(33)
	v_mfma_f32_16x16x32_bf16 v[0:3], v[240:243], v[168:171], v[0:3]
	s_waitcnt vmcnt(31)
	v_mfma_f32_16x16x32_bf16 v[4:7], v[240:243], v[172:175], v[4:7]
	s_waitcnt vmcnt(29)
	v_mfma_f32_16x16x32_bf16 v[8:11], v[240:243], v[176:179], v[8:11]
	s_waitcnt vmcnt(27)
	v_mfma_f32_16x16x32_bf16 v[12:15], v[240:243], v[180:183], v[12:15]
	s_waitcnt vmcnt(25)
	v_mfma_f32_16x16x32_bf16 v[16:19], v[240:243], v[184:187], v[16:19]
	s_waitcnt vmcnt(23)
	v_mfma_f32_16x16x32_bf16 v[20:23], v[240:243], v[188:191], v[20:23]
	s_waitcnt vmcnt(21)
	v_mfma_f32_16x16x32_bf16 v[24:27], v[240:243], v[192:195], v[24:27]
	s_waitcnt vmcnt(19)
	v_mfma_f32_16x16x32_bf16 v[28:31], v[240:243], v[208:211], v[28:31]
	s_waitcnt vmcnt(18)
	v_mfma_f32_16x16x32_bf16 v[0:3], v[244:247], v[212:215], v[0:3]
	v_mfma_f32_16x16x32_bf16 v[4:7], v[244:247], v[216:219], v[4:7]
	v_mfma_f32_16x16x32_bf16 v[8:11], v[244:247], v[220:223], v[8:11]
	v_mfma_f32_16x16x32_bf16 v[12:15], v[244:247], v[224:227], v[12:15]
	v_mfma_f32_16x16x32_bf16 v[16:19], v[244:247], v[228:231], v[16:19]
	v_mfma_f32_16x16x32_bf16 v[20:23], v[244:247], v[232:235], v[20:23]
	v_mfma_f32_16x16x32_bf16 v[24:27], v[244:247], v[236:239], v[24:27]
	v_mfma_f32_16x16x32_bf16 v[28:31], v[244:247], v[248:251], v[28:31]
	v_ashrrev_i32_e32 v40, 1, v58
	v_mad_i64_i32 v[40:41], s[22:23], v40, s63, v[36:37]
	v_add_u32_e32 v59, 1, v58
	v_ashrrev_i32_e32 v59, 1, v59
	v_mad_i64_i32 v[42:43], s[22:23], v59, s63, v[36:37]
	global_load_dwordx4 v[240:243], v[40:41], off
	global_load_dwordx4 v[244:247], v[42:43], off offset:64
	v_lshl_add_u64 v[44:45], v[38:39], 0, s[12:13]
	s_mov_b32 s14, 0x3100000
	v_add_co_u32_e32 v132, vcc, s14, v44
	s_nop 1
	v_addc_co_u32_e32 v133, vcc, 0, v45, vcc
	global_load_dwordx4 v[168:171], v[132:133], off
	global_load_dwordx4 v[212:215], v[132:133], off offset:64
	s_mov_b32 s14, 0x3110000
	v_add_co_u32_e32 v134, vcc, s14, v44
	s_nop 1
	v_addc_co_u32_e32 v135, vcc, 0, v45, vcc
	global_load_dwordx4 v[172:175], v[134:135], off
	global_load_dwordx4 v[216:219], v[134:135], off offset:64
	s_mov_b32 s14, 0x3120000
	v_add_co_u32_e32 v136, vcc, s14, v44
	s_nop 1
	v_addc_co_u32_e32 v137, vcc, 0, v45, vcc
	global_load_dwordx4 v[176:179], v[136:137], off
	global_load_dwordx4 v[220:223], v[136:137], off offset:64
	s_mov_b32 s14, 0x3130000
	v_add_co_u32_e32 v138, vcc, s14, v44
	s_nop 1
	v_addc_co_u32_e32 v139, vcc, 0, v45, vcc
	global_load_dwordx4 v[180:183], v[138:139], off
	global_load_dwordx4 v[224:227], v[138:139], off offset:64
	s_mov_b32 s14, 0x3140000
	v_add_co_u32_e32 v140, vcc, s14, v44
	s_nop 1
	v_addc_co_u32_e32 v141, vcc, 0, v45, vcc
	global_load_dwordx4 v[184:187], v[140:141], off
	global_load_dwordx4 v[228:231], v[140:141], off offset:64
	s_mov_b32 s14, 0x3150000
	v_add_co_u32_e32 v142, vcc, s14, v44
	s_nop 1
	v_addc_co_u32_e32 v143, vcc, 0, v45, vcc
	global_load_dwordx4 v[188:191], v[142:143], off
	global_load_dwordx4 v[232:235], v[142:143], off offset:64
	s_mov_b32 s14, 0x3160000
	v_add_co_u32_e32 v144, vcc, s14, v44
	s_nop 1
	v_addc_co_u32_e32 v145, vcc, 0, v45, vcc
	global_load_dwordx4 v[192:195], v[144:145], off
	global_load_dwordx4 v[236:239], v[144:145], off offset:64
	s_mov_b32 s14, 0x3170000
	v_add_co_u32_e32 v146, vcc, s14, v44
	s_nop 1
	v_addc_co_u32_e32 v147, vcc, 0, v45, vcc
	global_load_dwordx4 v[208:211], v[146:147], off
	global_load_dwordx4 v[248:251], v[146:147], off offset:64
	s_add_u32 s12, s12, 0x80
	s_addc_u32 s13, s13, 0
	v_add_u32_e32 v58, 2, v58
	s_waitcnt vmcnt(33)
	v_mfma_f32_16x16x32_bf16 v[0:3], v[60:63], v[68:71], v[0:3]
	s_waitcnt vmcnt(31)
	v_mfma_f32_16x16x32_bf16 v[4:7], v[60:63], v[72:75], v[4:7]
	s_waitcnt vmcnt(29)
	v_mfma_f32_16x16x32_bf16 v[8:11], v[60:63], v[76:79], v[8:11]
	s_waitcnt vmcnt(27)
	v_mfma_f32_16x16x32_bf16 v[12:15], v[60:63], v[80:83], v[12:15]
	s_waitcnt vmcnt(25)
	v_mfma_f32_16x16x32_bf16 v[16:19], v[60:63], v[84:87], v[16:19]
	s_waitcnt vmcnt(23)
	v_mfma_f32_16x16x32_bf16 v[20:23], v[60:63], v[88:91], v[20:23]
	s_waitcnt vmcnt(21)
	v_mfma_f32_16x16x32_bf16 v[24:27], v[60:63], v[92:95], v[24:27]
	s_waitcnt vmcnt(19)
	v_mfma_f32_16x16x32_bf16 v[28:31], v[60:63], v[96:99], v[28:31]
	s_waitcnt vmcnt(18)
	v_mfma_f32_16x16x32_bf16 v[0:3], v[64:67], v[100:103], v[0:3]
	v_mfma_f32_16x16x32_bf16 v[4:7], v[64:67], v[104:107], v[4:7]
	v_mfma_f32_16x16x32_bf16 v[8:11], v[64:67], v[108:111], v[8:11]
	v_mfma_f32_16x16x32_bf16 v[12:15], v[64:67], v[112:115], v[12:15]
	v_mfma_f32_16x16x32_bf16 v[16:19], v[64:67], v[116:119], v[16:19]
	v_mfma_f32_16x16x32_bf16 v[20:23], v[64:67], v[120:123], v[20:23]
	v_mfma_f32_16x16x32_bf16 v[24:27], v[64:67], v[124:127], v[24:27]
	v_mfma_f32_16x16x32_bf16 v[28:31], v[64:67], v[128:131], v[28:31]
	s_waitcnt vmcnt(15)
	v_mfma_f32_16x16x32_bf16 v[0:3], v[240:243], v[168:171], v[0:3]
	s_waitcnt vmcnt(13)
	v_mfma_f32_16x16x32_bf16 v[4:7], v[240:243], v[172:175], v[4:7]
	s_waitcnt vmcnt(11)
	v_mfma_f32_16x16x32_bf16 v[8:11], v[240:243], v[176:179], v[8:11]
	s_waitcnt vmcnt(9)
	v_mfma_f32_16x16x32_bf16 v[12:15], v[240:243], v[180:183], v[12:15]
	s_waitcnt vmcnt(7)
	v_mfma_f32_16x16x32_bf16 v[16:19], v[240:243], v[184:187], v[16:19]
	s_waitcnt vmcnt(5)
	v_mfma_f32_16x16x32_bf16 v[20:23], v[240:243], v[188:191], v[20:23]
	s_waitcnt vmcnt(3)
	v_mfma_f32_16x16x32_bf16 v[24:27], v[240:243], v[192:195], v[24:27]
	s_waitcnt vmcnt(1)
	v_mfma_f32_16x16x32_bf16 v[28:31], v[240:243], v[208:211], v[28:31]
	s_waitcnt vmcnt(0)
	v_mfma_f32_16x16x32_bf16 v[0:3], v[244:247], v[212:215], v[0:3]
	v_mfma_f32_16x16x32_bf16 v[4:7], v[244:247], v[216:219], v[4:7]
	v_mfma_f32_16x16x32_bf16 v[8:11], v[244:247], v[220:223], v[8:11]
	v_mfma_f32_16x16x32_bf16 v[12:15], v[244:247], v[224:227], v[12:15]
	v_mfma_f32_16x16x32_bf16 v[16:19], v[244:247], v[228:231], v[16:19]
	v_mfma_f32_16x16x32_bf16 v[20:23], v[244:247], v[232:235], v[20:23]
	v_mfma_f32_16x16x32_bf16 v[24:27], v[244:247], v[236:239], v[24:27]
	v_mfma_f32_16x16x32_bf16 v[28:31], v[244:247], v[248:251], v[28:31]
	s_or_b32 s12, s20, s17
	s_ashr_i32 s13, s12, 31
	s_lshl_b64 s[20:21], s[12:13], 14
	s_lshl_b32 s22, s12, 7
	v_readlane_b32 s12, v253, 47
	s_add_u32 s12, s12, s20
	v_readlane_b32 s13, v253, 48
	s_addc_u32 s13, s13, s21
	s_ashr_i32 s23, s22, 31
	v_lshlrev_b32_e32 v36, 2, v35
	v_lshlrev_b32_e32 v37, 11, v33
	v_lshlrev_b32_e32 v38, 9, v57
	s_lshl_b64 s[20:21], s[22:23], 2
	v_readlane_b32 s22, v253, 49
	v_or3_b32 v37, v37, v38, v36
	v_readlane_b32 s23, v253, 50
	s_add_u32 s20, s22, s20
	ds_write2_b32 v37, v0, v4 offset1:16
	ds_write2_b32 v37, v1, v5 offset0:128 offset1:144
	v_add_u32_e32 v0, 0x400, v37
	s_addc_u32 s21, s23, s21
	v_lshlrev_b32_e32 v5, 5, v35
	ds_write2_b32 v0, v2, v6 offset1:16
	ds_write2_b32 v0, v3, v7 offset0:128 offset1:144
	ds_write2_b32 v37, v8, v12 offset0:32 offset1:48
	ds_write2_b32 v37, v9, v13 offset0:160 offset1:176
	ds_write2_b32 v0, v10, v14 offset0:32 offset1:48
	ds_write2_b32 v0, v11, v15 offset0:160 offset1:176
	ds_write2_b32 v37, v16, v20 offset0:64 offset1:80
	ds_write2_b32 v37, v17, v21 offset0:192 offset1:208
	ds_write2_b32 v0, v18, v22 offset0:64 offset1:80
	ds_write2_b32 v0, v19, v23 offset0:192 offset1:208
	ds_write2_b32 v37, v24, v28 offset0:96 offset1:112
	ds_write2_b32 v37, v25, v29 offset0:224 offset1:240
	ds_write2_b32 v0, v26, v30 offset0:96 offset1:112
	ds_write2_b32 v0, v27, v31 offset0:224 offset1:240
	s_waitcnt lgkmcnt(0)
	s_barrier
	global_load_dwordx4 v[0:3], v5, s[20:21] offset:16
	global_load_dwordx4 v[6:9], v5, s[20:21]
	v_ashrrev_i32_e32 v4, 4, v56
	v_lshl_or_b32 v5, v4, 9, v5
	ds_read_b128 v[10:13], v5
	ds_read_b128 v[14:17], v5 offset:16
	s_movk_i32 s14, 0x110
	v_lshlrev_b32_e32 v152, 1, v34
	s_waitcnt vmcnt(1) lgkmcnt(0)
	v_add_f32_e32 v14, v0, v14
	s_waitcnt vmcnt(0)
	v_add_f32_e32 v10, v6, v10
	v_add_f32_e32 v11, v7, v11
	v_add_f32_e32 v12, v8, v12
	v_add_f32_e32 v13, v9, v13
	v_add_f32_e32 v15, v1, v15
	v_add_f32_e32 v16, v2, v16
	v_add_f32_e32 v17, v3, v17
	ds_read_b128 v[0:3], v5 offset:8192
	ds_read_b128 v[6:9], v5 offset:8208
	s_waitcnt lgkmcnt(1)
	v_add_f32_e32 v10, v10, v0
	v_add_f32_e32 v11, v11, v1
	v_add_f32_e32 v12, v12, v2
	v_add_f32_e32 v13, v13, v3
	s_waitcnt lgkmcnt(0)
	v_add_f32_e32 v14, v14, v6
	v_add_f32_e32 v15, v15, v7
	v_add_f32_e32 v16, v16, v8
	v_add_f32_e32 v17, v17, v9
	ds_read_b128 v[0:3], v5 offset:16384
	ds_read_b128 v[6:9], v5 offset:16400
	s_waitcnt lgkmcnt(1)
	v_add_f32_e32 v10, v10, v0
	v_add_f32_e32 v11, v11, v1
	v_add_f32_e32 v12, v12, v2
	v_add_f32_e32 v13, v13, v3
	s_waitcnt lgkmcnt(0)
	v_add_f32_e32 v14, v14, v6
	v_add_f32_e32 v15, v15, v7
	v_add_f32_e32 v16, v16, v8
	v_add_f32_e32 v17, v17, v9
	ds_read_b128 v[0:3], v5 offset:24576
	ds_read_b128 v[6:9], v5 offset:24592
	s_waitcnt lgkmcnt(1)
	v_add_f32_e32 v0, v10, v0
	v_add_f32_e32 v10, v12, v2
	s_waitcnt lgkmcnt(0)
	v_add_f32_e32 v2, v15, v7
	v_mul_f32_e32 v7, 0x3d372713, v0
	v_mul_f32_e32 v7, v0, v7
	v_fma_f32 v7, v0, v7, v0
	v_mul_f32_e32 v7, 0x3f4c422a, v7
	v_add_f32_e32 v7, v7, v7
	v_mul_f32_e32 v7, 0x3fb8aa3b, v7
	v_exp_f32_e32 v7, v7
	v_add_f32_e32 v5, v16, v8
	v_add_f32_e32 v1, v11, v1
	v_add_f32_e32 v11, v13, v3
	v_add_f32_e32 v7, 1.0, v7
	v_div_scale_f32 v8, s[20:21], v7, v7, 2.0
	v_add_f32_e32 v3, v17, v9
	v_rcp_f32_e32 v9, v8
	v_add_f32_e32 v6, v14, v6
	v_mul_f32_e32 v0, 0.5, v0
	v_mad_u32_u24 v16, v35, s14, v152
	v_fma_f32 v12, -v8, v9, 1.0
	v_fmac_f32_e32 v9, v12, v9
	v_div_scale_f32 v12, vcc, 2.0, v7, 2.0
	v_mul_f32_e32 v13, v12, v9
	v_fma_f32 v14, -v8, v13, v12
	v_fmac_f32_e32 v13, v14, v9
	v_fma_f32 v8, -v8, v13, v12
	v_div_fmas_f32 v8, v8, v9, v13
	v_div_fixup_f32 v7, v8, v7, 2.0
	v_sub_f32_e32 v7, 1.0, v7
	v_add_f32_e32 v7, 1.0, v7
	v_mul_f32_e32 v0, v0, v7
	v_mul_f32_e32 v7, 0x3d372713, v1
	v_mul_f32_e32 v7, v1, v7
	v_fma_f32 v7, v1, v7, v1
	v_mul_f32_e32 v7, 0x3f4c422a, v7
	v_add_f32_e32 v7, v7, v7
	v_mul_f32_e32 v7, 0x3fb8aa3b, v7
	v_exp_f32_e32 v7, v7
	v_mul_f32_e32 v1, 0.5, v1
	v_add_f32_e32 v7, 1.0, v7
	v_div_scale_f32 v8, s[20:21], v7, v7, 2.0
	v_rcp_f32_e32 v9, v8
	s_nop 0
	v_fma_f32 v12, -v8, v9, 1.0
	v_fmac_f32_e32 v9, v12, v9
	v_div_scale_f32 v12, vcc, 2.0, v7, 2.0
	v_mul_f32_e32 v13, v12, v9
	v_fma_f32 v14, -v8, v13, v12
	v_fmac_f32_e32 v13, v14, v9
	v_fma_f32 v8, -v8, v13, v12
	v_div_fmas_f32 v8, v8, v9, v13
	v_div_fixup_f32 v7, v8, v7, 2.0
	v_sub_f32_e32 v7, 1.0, v7
	v_add_f32_e32 v7, 1.0, v7
	v_mul_f32_e32 v1, v1, v7
	v_cvt_pk_bf16_f32 v0, v0, v1
	v_mul_f32_e32 v1, 0x3d372713, v10
	v_mul_f32_e32 v1, v10, v1
	v_fma_f32 v1, v10, v1, v10
	v_mul_f32_e32 v1, 0x3f4c422a, v1
	v_add_f32_e32 v1, v1, v1
	v_mul_f32_e32 v1, 0x3fb8aa3b, v1
	v_exp_f32_e32 v1, v1
	s_nop 0
	v_add_f32_e32 v1, 1.0, v1
	v_div_scale_f32 v7, s[20:21], v1, v1, 2.0
	v_rcp_f32_e32 v8, v7
	s_nop 0
	v_fma_f32 v9, -v7, v8, 1.0
	v_fmac_f32_e32 v8, v9, v8
	v_div_scale_f32 v9, vcc, 2.0, v1, 2.0
	v_mul_f32_e32 v12, v9, v8
	v_fma_f32 v13, -v7, v12, v9
	v_fmac_f32_e32 v12, v13, v8
	v_fma_f32 v7, -v7, v12, v9
	v_div_fmas_f32 v7, v7, v8, v12
	v_div_fixup_f32 v1, v7, v1, 2.0
	v_sub_f32_e32 v1, 1.0, v1
	v_mul_f32_e32 v7, 0.5, v10
	v_add_f32_e32 v1, 1.0, v1
	v_mul_f32_e32 v1, v7, v1
	v_mul_f32_e32 v7, 0x3d372713, v11
	v_mul_f32_e32 v7, v11, v7
	v_fma_f32 v7, v11, v7, v11
	v_mul_f32_e32 v7, 0x3f4c422a, v7
	v_add_f32_e32 v7, v7, v7
	v_mul_f32_e32 v7, 0x3fb8aa3b, v7
	v_exp_f32_e32 v7, v7
	s_nop 0
	v_add_f32_e32 v7, 1.0, v7
	v_div_scale_f32 v8, s[20:21], v7, v7, 2.0
	v_rcp_f32_e32 v9, v8
	s_nop 0
	v_fma_f32 v10, -v8, v9, 1.0
	v_fmac_f32_e32 v9, v10, v9
	v_div_scale_f32 v10, vcc, 2.0, v7, 2.0
	v_mul_f32_e32 v12, v10, v9
	v_fma_f32 v13, -v8, v12, v10
	v_fmac_f32_e32 v12, v13, v9
	v_fma_f32 v8, -v8, v12, v10
	v_div_fmas_f32 v8, v8, v9, v12
	v_div_fixup_f32 v7, v8, v7, 2.0
	v_sub_f32_e32 v7, 1.0, v7
	v_mul_f32_e32 v8, 0.5, v11
	v_add_f32_e32 v7, 1.0, v7
	v_mul_f32_e32 v7, v8, v7
	v_cvt_pk_bf16_f32 v1, v1, v7
	v_mul_f32_e32 v7, 0x3d372713, v6
	v_mul_f32_e32 v7, v6, v7
	v_fma_f32 v7, v6, v7, v6
	v_mul_f32_e32 v7, 0x3f4c422a, v7
	v_add_f32_e32 v7, v7, v7
	v_mul_f32_e32 v7, 0x3fb8aa3b, v7
	v_exp_f32_e32 v7, v7
	v_mul_f32_e32 v6, 0.5, v6
	v_add_f32_e32 v7, 1.0, v7
	v_div_scale_f32 v8, s[20:21], v7, v7, 2.0
	v_rcp_f32_e32 v9, v8
	s_nop 0
	v_fma_f32 v10, -v8, v9, 1.0
	v_fmac_f32_e32 v9, v10, v9
	v_div_scale_f32 v10, vcc, 2.0, v7, 2.0
	v_mul_f32_e32 v11, v10, v9
	v_fma_f32 v12, -v8, v11, v10
	v_fmac_f32_e32 v11, v12, v9
	v_fma_f32 v8, -v8, v11, v10
	v_div_fmas_f32 v8, v8, v9, v11
	v_div_fixup_f32 v7, v8, v7, 2.0
	v_sub_f32_e32 v7, 1.0, v7
	v_add_f32_e32 v7, 1.0, v7
	v_mul_f32_e32 v6, v6, v7
	v_mul_f32_e32 v7, 0x3d372713, v2
	v_mul_f32_e32 v7, v2, v7
	v_fma_f32 v7, v2, v7, v2
	v_mul_f32_e32 v7, 0x3f4c422a, v7
	v_add_f32_e32 v7, v7, v7
	v_mul_f32_e32 v7, 0x3fb8aa3b, v7
	v_exp_f32_e32 v7, v7
	v_mul_f32_e32 v2, 0.5, v2
	v_add_f32_e32 v7, 1.0, v7
	v_div_scale_f32 v8, s[20:21], v7, v7, 2.0
	v_rcp_f32_e32 v9, v8
	s_nop 0
	v_fma_f32 v10, -v8, v9, 1.0
	v_fmac_f32_e32 v9, v10, v9
	v_div_scale_f32 v10, vcc, 2.0, v7, 2.0
	v_mul_f32_e32 v11, v10, v9
	v_fma_f32 v12, -v8, v11, v10
	v_fmac_f32_e32 v11, v12, v9
	v_fma_f32 v8, -v8, v11, v10
	v_div_fmas_f32 v8, v8, v9, v11
	v_div_fixup_f32 v7, v8, v7, 2.0
	v_sub_f32_e32 v7, 1.0, v7
	v_add_f32_e32 v7, 1.0, v7
	v_mul_f32_e32 v2, v2, v7
	v_cvt_pk_bf16_f32 v2, v6, v2
	v_mul_f32_e32 v6, 0x3d372713, v5
	v_mul_f32_e32 v6, v5, v6
	v_fma_f32 v6, v5, v6, v5
	v_mul_f32_e32 v6, 0x3f4c422a, v6
	v_add_f32_e32 v6, v6, v6
	v_mul_f32_e32 v6, 0x3fb8aa3b, v6
	v_exp_f32_e32 v6, v6
	v_mul_f32_e32 v5, 0.5, v5
	v_add_f32_e32 v6, 1.0, v6
	v_div_scale_f32 v7, s[20:21], v6, v6, 2.0
	v_rcp_f32_e32 v8, v7
	s_nop 0
	v_fma_f32 v9, -v7, v8, 1.0
	v_fmac_f32_e32 v8, v9, v8
	v_div_scale_f32 v9, vcc, 2.0, v6, 2.0
	v_mul_f32_e32 v10, v9, v8
	v_fma_f32 v11, -v7, v10, v9
	v_fmac_f32_e32 v10, v11, v8
	v_fma_f32 v7, -v7, v10, v9
	v_div_fmas_f32 v7, v7, v8, v10
	v_div_fixup_f32 v6, v7, v6, 2.0
	v_sub_f32_e32 v6, 1.0, v6
	v_add_f32_e32 v6, 1.0, v6
	v_mul_f32_e32 v5, v5, v6
	v_mul_f32_e32 v6, 0x3d372713, v3
	v_mul_f32_e32 v6, v3, v6
	v_fma_f32 v6, v3, v6, v3
	v_mul_f32_e32 v6, 0x3f4c422a, v6
	v_add_f32_e32 v6, v6, v6
	v_mul_f32_e32 v6, 0x3fb8aa3b, v6
	v_exp_f32_e32 v6, v6
	v_mul_f32_e32 v3, 0.5, v3
	v_add_f32_e32 v6, 1.0, v6
	v_div_scale_f32 v7, s[20:21], v6, v6, 2.0
	v_rcp_f32_e32 v8, v7
	s_nop 0
	v_fma_f32 v9, -v7, v8, 1.0
	v_fmac_f32_e32 v8, v9, v8
	v_div_scale_f32 v9, vcc, 2.0, v6, 2.0
	v_mul_f32_e32 v10, v9, v8
	v_fma_f32 v11, -v7, v10, v9
	v_fmac_f32_e32 v10, v11, v8
	v_fma_f32 v7, -v7, v10, v9
	v_div_fmas_f32 v7, v7, v8, v10
	v_div_fixup_f32 v6, v7, v6, 2.0
	v_sub_f32_e32 v6, 1.0, v6
	v_add_f32_e32 v6, 1.0, v6
	v_mul_f32_e32 v3, v3, v6
	v_cvt_pk_bf16_f32 v3, v5, v3
	v_mul_lo_u32 v5, v4, s14
	v_lshl_add_u32 v6, v35, 4, v5
	ds_write_b128 v6, v[0:3] offset:32768
	v_or_b32_e32 v0, v57, v35
	v_ashrrev_i32_e32 v1, 31, v0
	v_lshlrev_b64 v[0:1], 8, v[0:1]
	v_lshl_add_u64 v[0:1], s[12:13], 0, v[0:1]
	v_lshl_add_u64 v[14:15], v[0:1], 0, v[152:153]
	s_waitcnt lgkmcnt(0)
	s_barrier
	global_load_dwordx4 v[6:9], v[14:15], off
	global_load_dwordx4 v[10:13], v[14:15], off offset:64
	ds_read_b128 v[0:3], v16 offset:32768
	s_waitcnt vmcnt(1) lgkmcnt(0)
	v_mfma_f32_16x16x32_bf16 v[0:3], v[0:3], v[6:9], 0
	ds_read_b128 v[6:9], v16 offset:32832
	s_lshl_b32 s12, s19, 15
	s_lshl_b32 s13, s18, 14
	s_waitcnt vmcnt(0) lgkmcnt(0)
	v_mfma_f32_16x16x32_bf16 v[0:3], v[6:9], v[10:13], v[0:3]
	global_load_dwordx4 v[10:13], v[14:15], off offset:128
	ds_read_b128 v[6:9], v16 offset:32896
	s_or_b32 s14, s12, s13
	s_waitcnt vmcnt(0) lgkmcnt(0)
	v_mfma_f32_16x16x32_bf16 v[0:3], v[6:9], v[10:13], v[0:3]
	global_load_dwordx4 v[10:13], v[14:15], off offset:192
	ds_read_b128 v[6:9], v16 offset:32960
	s_mov_b64 s[12:13], -1
	s_waitcnt vmcnt(0) lgkmcnt(0)
	v_mfma_f32_16x16x32_bf16 v[0:3], v[6:9], v[10:13], v[0:3]
	v_and_b32_e32 v6, 0xffffffc0, v56
	v_lshl_add_u32 v6, v33, 10, v6
	v_or_b32_e32 v6, v6, v36
	s_and_b64 vcc, exec, s[4:5]
	s_nop 3
	ds_write2st64_b32 v6, v0, v1 offset0:160 offset1:161
	ds_write2st64_b32 v6, v2, v3 offset0:162 offset1:163
	s_waitcnt lgkmcnt(0)
	s_barrier
	s_cbranch_vccz .LBB0_346
	v_lshlrev_b32_e32 v0, 2, v56
	v_and_b32_e32 v6, 12, v0
	v_lshlrev_b32_e32 v0, 2, v32
	v_lshl_add_u32 v2, v6, 8, v0
	ds_read2st64_b32 v[0:1], v2 offset0:162 offset1:163
	ds_read2st64_b32 v[2:3], v2 offset0:160 offset1:161
	s_lshl_b32 s4, s14, 1
	v_readlane_b32 s12, v253, 36
	v_or_b32_e32 v6, s15, v6
	s_add_u32 s4, s12, s4
	v_or_b32_e32 v7, 3, v6
	s_movk_i32 s12, 0xff
	v_cmp_gt_i32_e32 vcc, s12, v7
	v_readlane_b32 s13, v253, 37
	v_ashrrev_i32_e32 v33, 31, v32
	s_waitcnt lgkmcnt(1)
	v_cndmask_b32_e32 v1, 0, v1, vcc
	s_addc_u32 s5, s13, 0
	s_waitcnt lgkmcnt(0)
	v_cvt_pk_bf16_f32 v3, v2, v3
	v_cvt_pk_bf16_f32 v2, v0, v1
	v_lshlrev_b64 v[0:1], 9, v[32:33]
	v_lshl_add_u64 v[0:1], s[4:5], 0, v[0:1]
	v_ashrrev_i32_e32 v7, 31, v6
	v_lshl_add_u64 v[0:1], v[6:7], 1, v[0:1]
	global_store_dword v[0:1], v3, off
	s_mov_b64 s[12:13], 0
